# phase-2 q down-projection epilogue regenerated straight-line with 16-byte stores (same row-sum reduction order)
# speedup vs baseline: 1.0682x; 1.0013x over previous
; template <bool SWAP, class Epi, bool THIN = false> ...
;     ...
;     for (int st = 0; st < ns; ++st) {
;       asm volatile("s_waitcnt vmcnt(0)" ::: "memory");
;       __builtin_amdgcn_s_barrier();
;       asm volatile("" ::: "memory");
;       if (st + 1 < ns) {
;         char* nb = smem + ((st + 1) & 1) * 65536;
;         const int ko = (st + 1) * 64;
; #pragma unroll
;         for (int i = 0; i < 4; ++i) { GLDS16(A + (size_t)(ap[i] + ko), nb + tid * 16 + i * 8192); GLDS16(Bt + (size_t)(bp[i] + ko), nb + 32768 + tid * 16 + i * 8192); }
;       }
;       const char* sa = smem + (st & 1) * 65536 + (wr * 64 + fr) * 128;
;       const char* sb = smem + (st & 1) * 65536 + 32768 + (wc * 128 + fr) * 128;
;       if constexpr (THIN) {
;         if (wc == 0) {
; #pragma unroll
;           for (int ks = 0; ks < 2; ++ks) {
;             bf16x8 af[4], bf[2];
; #pragma unroll
;             for (int m = 0; m < 4; ++m) af[m] = *(const bf16x8*)(sa + m * 2048 + (((ks * 4 + fq) ^ swz) << 4));
; #pragma unroll
;             for (int n = 0; n < 2; ++n) bf[n] = *(const bf16x8*)(sb + n * 2048 + (((ks * 4 + fq) ^ swz) << 4));
; #pragma unroll
;             for (int m = 0; m < 4; ++m)
; #pragma unroll
;               for (int n = 0; n < 2; ++n)
;                 acc[m][n] = SWAP ? __builtin_amdgcn_mfma_f32_16x16x32_bf16(bf[n], af[m], acc[m][n], 0, 0, 0)
;                                  : __builtin_amdgcn_mfma_f32_16x16x32_bf16(af[m], bf[n], acc[m][n], 0, 0, 0);
;           }
;         }
;       } else {
;       bf16x8 afA[4], afB[4], bfb[2][2];
; #pragma unroll
;       for (int m = 0; m < 4; ++m) afA[m] = *(const bf16x8*)(sa + m * 2048 + ((fq ^ swz) << 4));
; #pragma unroll
;       for (int n = 0; n < 2; ++n) bfb[0][n] = *(const bf16x8*)(sb + n * 2048 + ((fq ^ swz) << 4));
; #pragma unroll
;       for (int gq = 0; gq < 8; ++gq) {
;         const int ks = gq >> 2, nh = gq & 3;
;         if (gq < 7) {
;           const int ks2 = (gq + 1) >> 2, nh2 = (gq + 1) & 3;
; #pragma unroll
;           for (int n = 0; n < 2; ++n) bfb[(gq + 1) & 1][n] = *(const bf16x8*)(sb + (nh2 * 2 + n) * 2048 + (((ks2 * 4 + fq) ^ swz) << 4));
;         }
;         if (gq == 3) {
; #pragma unroll
;           for (int m = 0; m < 4; ++m) afB[m] = *(const bf16x8*)(sa + m * 2048 + (((4 + fq) ^ swz) << 4));
;         }
;         __builtin_amdgcn_sched_barrier(0);
; #pragma unroll
.LBB0_339:
	s_add_i32 s8, s7, 0x10000
	s_and_b32 s9, s8, 0x10000
	v_add_u32_e32 v171, s9, v144
	s_nop 0
	v_readfirstlane_b32 s9, v171
	s_waitcnt vmcnt(0)
	s_barrier
	s_and_b32 s7, s7, 0x10000
	v_add_u32_e32 v130, s7, v145
	v_add_u32_e32 v140, v130, v147
	ds_read_b128 v[172:175], v140
	ds_read_b128 v[176:179], v140 offset:2048
	ds_read_b128 v[180:183], v140 offset:4096
	ds_read_b128 v[184:187], v140 offset:6144
	v_or_b32_e32 v140, s7, v146
	v_add_u32_e32 v141, v140, v147
	ds_read_b128 v[188:191], v141 offset:32768
	ds_read_b128 v[192:195], v141 offset:34816
	ds_read_b128 v[196:199], v141 offset:36864
	ds_read_b128 v[200:203], v141 offset:38912
	v_add_u32_e32 v130, v130, v148
	s_waitcnt lgkmcnt(3)
	v_mfma_f32_16x16x32_bf16 v[126:129], v[188:191], v[172:175], v[126:129]
	s_mov_b32 m0, s9
	v_mfma_f32_16x16x32_bf16 v[110:113], v[188:191], v[176:179], v[110:113]
	global_load_lds_dwordx4 v139, s[36:37]
	v_add_u32_e32 v139, 0x80, v139
	v_mfma_f32_16x16x32_bf16 v[82:85], v[188:191], v[180:183], v[82:85]
	v_mfma_f32_16x16x32_bf16 v[50:53], v[188:191], v[184:187], v[50:53]
	ds_read_b128 v[188:191], v141 offset:40960
	ds_read_b128 v[204:207], v141 offset:43008
	s_waitcnt lgkmcnt(4)
	v_mfma_f32_16x16x32_bf16 v[122:125], v[192:195], v[172:175], v[122:125]
	s_add_u32 m0, s9, 0x8000
	v_mfma_f32_16x16x32_bf16 v[106:109], v[192:195], v[176:179], v[106:109]
	global_load_lds_dwordx4 v138, s[22:23]
	v_add_u32_e32 v138, 0x80, v138
	v_mfma_f32_16x16x32_bf16 v[78:81], v[192:195], v[180:183], v[78:81]
	v_mfma_f32_16x16x32_bf16 v[42:45], v[192:195], v[184:187], v[42:45]
	s_waitcnt lgkmcnt(3)
	v_mfma_f32_16x16x32_bf16 v[118:121], v[196:199], v[172:175], v[118:121]
	s_add_u32 m0, s9, 0x2000
	v_mfma_f32_16x16x32_bf16 v[94:97], v[196:199], v[176:179], v[94:97]
	global_load_lds_dwordx4 v137, s[36:37]
	v_add_u32_e32 v137, 0x80, v137
	v_mfma_f32_16x16x32_bf16 v[58:61], v[196:199], v[180:183], v[58:61]
	v_mfma_f32_16x16x32_bf16 v[26:29], v[196:199], v[184:187], v[26:29]
	ds_read_b128 v[192:195], v141 offset:45056
	ds_read_b128 v[196:199], v141 offset:47104
	s_waitcnt lgkmcnt(4)
	v_mfma_f32_16x16x32_bf16 v[114:117], v[200:203], v[172:175], v[114:117]
	s_add_u32 m0, s9, 0xa000
	v_mfma_f32_16x16x32_bf16 v[86:89], v[200:203], v[176:179], v[86:89]
	global_load_lds_dwordx4 v136, s[22:23]
	v_add_u32_e32 v136, 0x80, v136
	v_mfma_f32_16x16x32_bf16 v[54:57], v[200:203], v[180:183], v[54:57]
	v_mfma_f32_16x16x32_bf16 v[22:25], v[200:203], v[184:187], v[22:25]
	v_add_u32_e32 v140, v140, v148
	s_waitcnt lgkmcnt(3)
	v_mfma_f32_16x16x32_bf16 v[102:105], v[188:191], v[172:175], v[102:105]
	ds_read_b128 v[200:203], v140 offset:32768
	ds_read_b128 v[208:211], v140 offset:34816
	s_add_u32 m0, s9, 0x4000
	v_mfma_f32_16x16x32_bf16 v[74:77], v[188:191], v[176:179], v[74:77]
	global_load_lds_dwordx4 v135, s[36:37]
	v_add_u32_e32 v135, 0x80, v135
	v_mfma_f32_16x16x32_bf16 v[46:49], v[188:191], v[180:183], v[46:49]
	v_mfma_f32_16x16x32_bf16 v[10:13], v[188:191], v[184:187], v[10:13]
	ds_read_b128 v[188:191], v130
	ds_read_b128 v[212:215], v130 offset:2048
	ds_read_b128 v[216:219], v130 offset:4096
	ds_read_b128 v[220:223], v130 offset:6144
	s_waitcnt lgkmcnt(8)
	v_mfma_f32_16x16x32_bf16 v[98:101], v[204:207], v[172:175], v[98:101]
	s_add_u32 m0, s9, 0xc000
	v_mfma_f32_16x16x32_bf16 v[66:69], v[204:207], v[176:179], v[66:69]
	global_load_lds_dwordx4 v134, s[22:23]
	v_add_u32_e32 v134, 0x80, v134
	v_mfma_f32_16x16x32_bf16 v[30:33], v[204:207], v[180:183], v[30:33]
	v_mfma_f32_16x16x32_bf16 v[6:9], v[204:207], v[184:187], v[6:9]
	s_waitcnt lgkmcnt(7)
	v_mfma_f32_16x16x32_bf16 v[70:73], v[192:195], v[172:175], v[70:73]
	s_add_u32 m0, s9, 0x6000
	s_waitcnt lgkmcnt(6)
	v_mfma_f32_16x16x32_bf16 v[62:65], v[196:199], v[172:175], v[62:65]
	global_load_lds_dwordx4 v133, s[36:37]
	v_add_u32_e32 v133, 0x80, v133
	v_mfma_f32_16x16x32_bf16 v[38:41], v[192:195], v[176:179], v[38:41]
	v_mfma_f32_16x16x32_bf16 v[34:37], v[196:199], v[176:179], v[34:37]
	ds_read_b128 v[172:175], v140 offset:36864
	ds_read_b128 v[176:179], v140 offset:38912
	v_mfma_f32_16x16x32_bf16 v[18:21], v[192:195], v[180:183], v[18:21]
	s_add_u32 m0, s9, 0xe000
	v_mfma_f32_16x16x32_bf16 v[14:17], v[196:199], v[180:183], v[14:17]
	global_load_lds_dwordx4 v132, s[22:23]
	v_add_u32_e32 v132, 0x80, v132
	v_mfma_f32_16x16x32_bf16 v[2:5], v[192:195], v[184:187], v[2:5]
	v_mfma_f32_16x16x32_bf16 v[90:93], v[196:199], v[184:187], v[90:93]
	ds_read_b128 v[180:183], v140 offset:40960
	ds_read_b128 v[184:187], v140 offset:43008
	s_waitcnt lgkmcnt(7)
	v_mfma_f32_16x16x32_bf16 v[126:129], v[200:203], v[188:191], v[126:129]
	v_mfma_f32_16x16x32_bf16 v[122:125], v[208:211], v[188:191], v[122:125]
	s_waitcnt lgkmcnt(6)
	v_mfma_f32_16x16x32_bf16 v[110:113], v[200:203], v[212:215], v[110:113]
	v_mfma_f32_16x16x32_bf16 v[106:109], v[208:211], v[212:215], v[106:109]
	s_waitcnt lgkmcnt(5)
	v_mfma_f32_16x16x32_bf16 v[82:85], v[200:203], v[216:219], v[82:85]
	v_mfma_f32_16x16x32_bf16 v[78:81], v[208:211], v[216:219], v[78:81]
	s_waitcnt lgkmcnt(4)
	v_mfma_f32_16x16x32_bf16 v[50:53], v[200:203], v[220:223], v[50:53]
	v_mfma_f32_16x16x32_bf16 v[42:45], v[208:211], v[220:223], v[42:45]
	s_waitcnt lgkmcnt(3)
	v_mfma_f32_16x16x32_bf16 v[118:121], v[172:175], v[188:191], v[118:121]
	v_mfma_f32_16x16x32_bf16 v[94:97], v[172:175], v[212:215], v[94:97]
	v_mfma_f32_16x16x32_bf16 v[58:61], v[172:175], v[216:219], v[58:61]
	v_mfma_f32_16x16x32_bf16 v[26:29], v[172:175], v[220:223], v[26:29]
	ds_read_b128 v[172:175], v140 offset:45056
	ds_read_b128 v[192:195], v140 offset:47104
	s_waitcnt lgkmcnt(4)
; template <bool SWAP, class Epi, bool THIN = false> ...
;     ...
;     for (int st = 0; st < ns; ++st) {
;       asm volatile("s_waitcnt vmcnt(0)" ::: "memory");
;       __builtin_amdgcn_s_barrier();
;       asm volatile("" ::: "memory");
;       if (st + 1 < ns) {
;         char* nb = smem + ((st + 1) & 1) * 65536;
;         const int ko = (st + 1) * 64;
; #pragma unroll
;         for (int i = 0; i < 4; ++i) { GLDS16(A + (size_t)(ap[i] + ko), nb + tid * 16 + i * 8192); GLDS16(Bt + (size_t)(bp[i] + ko), nb + 32768 + tid * 16 + i * 8192); }
;       }
;       const char* sa = smem + (st & 1) * 65536 + (wr * 64 + fr) * 128;
;       const char* sb = smem + (st & 1) * 65536 + 32768 + (wc * 128 + fr) * 128;
;       if constexpr (THIN) {
;         if (wc == 0) {
; #pragma unroll
;           for (int ks = 0; ks < 2; ++ks) {
;             bf16x8 af[4], bf[2];
; #pragma unroll
;             for (int m = 0; m < 4; ++m) af[m] = *(const bf16x8*)(sa + m * 2048 + (((ks * 4 + fq) ^ swz) << 4));
; #pragma unroll
;             for (int n = 0; n < 2; ++n) bf[n] = *(const bf16x8*)(sb + n * 2048 + (((ks * 4 + fq) ^ swz) << 4));
; #pragma unroll
;             for (int m = 0; m < 4; ++m)
; #pragma unroll
;               for (int n = 0; n < 2; ++n)
;                 acc[m][n] = SWAP ? __builtin_amdgcn_mfma_f32_16x16x32_bf16(bf[n], af[m], acc[m][n], 0, 0, 0)
;                                  : __builtin_amdgcn_mfma_f32_16x16x32_bf16(af[m], bf[n], acc[m][n], 0, 0, 0);
;           }
;         }
;       } else {
;       bf16x8 afA[4], afB[4], bfb[2][2];
; #pragma unroll
;       for (int m = 0; m < 4; ++m) afA[m] = *(const bf16x8*)(sa + m * 2048 + ((fq ^ swz) << 4));
; #pragma unroll
;       for (int n = 0; n < 2; ++n) bfb[0][n] = *(const bf16x8*)(sb + n * 2048 + ((fq ^ swz) << 4));
; #pragma unroll
;       for (int gq = 0; gq < 8; ++gq) {
;         const int ks = gq >> 2, nh = gq & 3;
;         if (gq < 7) {
;           const int ks2 = (gq + 1) >> 2, nh2 = (gq + 1) & 3;
; #pragma unroll
;           for (int n = 0; n < 2; ++n) bfb[(gq + 1) & 1][n] = *(const bf16x8*)(sb + (nh2 * 2 + n) * 2048 + (((ks2 * 4 + fq) ^ swz) << 4));
;         }
;         if (gq == 3) {
; #pragma unroll
;           for (int m = 0; m < 4; ++m) afB[m] = *(const bf16x8*)(sa + m * 2048 + (((4 + fq) ^ swz) << 4));
;         }
;         __builtin_amdgcn_sched_barrier(0);
; #pragma unroll
	v_mfma_f32_16x16x32_bf16 v[114:117], v[176:179], v[188:191], v[114:117]
	v_mfma_f32_16x16x32_bf16 v[86:89], v[176:179], v[212:215], v[86:89]
	v_mfma_f32_16x16x32_bf16 v[54:57], v[176:179], v[216:219], v[54:57]
	v_mfma_f32_16x16x32_bf16 v[22:25], v[176:179], v[220:223], v[22:25]
	s_waitcnt lgkmcnt(3)
	v_mfma_f32_16x16x32_bf16 v[102:105], v[180:183], v[188:191], v[102:105]
	s_waitcnt lgkmcnt(2)
	v_mfma_f32_16x16x32_bf16 v[98:101], v[184:187], v[188:191], v[98:101]
	v_mfma_f32_16x16x32_bf16 v[74:77], v[180:183], v[212:215], v[74:77]
	v_mfma_f32_16x16x32_bf16 v[66:69], v[184:187], v[212:215], v[66:69]
	v_mfma_f32_16x16x32_bf16 v[46:49], v[180:183], v[216:219], v[46:49]
	v_mfma_f32_16x16x32_bf16 v[30:33], v[184:187], v[216:219], v[30:33]
	v_mfma_f32_16x16x32_bf16 v[10:13], v[180:183], v[220:223], v[10:13]
	v_mfma_f32_16x16x32_bf16 v[6:9], v[184:187], v[220:223], v[6:9]
	s_waitcnt lgkmcnt(1)
	v_mfma_f32_16x16x32_bf16 v[70:73], v[172:175], v[188:191], v[70:73]
	s_add_i32 s6, s6, 64
	s_cmpk_eq_i32 s6, 0x3c0
	s_mov_b32 s7, s8
	s_waitcnt lgkmcnt(0)
	v_mfma_f32_16x16x32_bf16 v[62:65], v[192:195], v[188:191], v[62:65]
	v_mfma_f32_16x16x32_bf16 v[38:41], v[172:175], v[212:215], v[38:41]
	v_mfma_f32_16x16x32_bf16 v[34:37], v[192:195], v[212:215], v[34:37]
	v_mfma_f32_16x16x32_bf16 v[18:21], v[172:175], v[216:219], v[18:21]
	v_mfma_f32_16x16x32_bf16 v[14:17], v[192:195], v[216:219], v[14:17]
	v_mfma_f32_16x16x32_bf16 v[2:5], v[172:175], v[220:223], v[2:5]
	v_mfma_f32_16x16x32_bf16 v[90:93], v[192:195], v[220:223], v[90:93]
	s_cbranch_scc0 .LBB0_339
	s_waitcnt vmcnt(0)
	s_barrier
	v_add_u32_e32 v130, v159, v147
	ds_read_b128 v[132:135], v130
	ds_read_b128 v[136:139], v130 offset:2048
	ds_read_b128 v[172:175], v130 offset:4096
	ds_read_b128 v[176:179], v130 offset:6144
	v_add_u32_e32 v130, v160, v147
	ds_read_b128 v[180:183], v130
	ds_read_b128 v[184:187], v130 offset:2048
	ds_read_b128 v[188:191], v130 offset:4096
	ds_read_b128 v[192:195], v130 offset:6144
	s_waitcnt lgkmcnt(0)
	v_mfma_f32_16x16x32_bf16 v[126:129], v[180:183], v[132:135], v[126:129]
	v_mfma_f32_16x16x32_bf16 v[110:113], v[180:183], v[136:139], v[110:113]
	v_mfma_f32_16x16x32_bf16 v[82:85], v[180:183], v[172:175], v[82:85]
	v_mfma_f32_16x16x32_bf16 v[50:53], v[180:183], v[176:179], v[50:53]
	ds_read_b128 v[180:183], v130 offset:8192
	ds_read_b128 v[196:199], v130 offset:10240
	v_mfma_f32_16x16x32_bf16 v[122:125], v[184:187], v[132:135], v[122:125]
	v_mfma_f32_16x16x32_bf16 v[106:109], v[184:187], v[136:139], v[106:109]
	v_mfma_f32_16x16x32_bf16 v[78:81], v[184:187], v[172:175], v[78:81]
	v_mfma_f32_16x16x32_bf16 v[42:45], v[184:187], v[176:179], v[42:45]
	v_mfma_f32_16x16x32_bf16 v[118:121], v[188:191], v[132:135], v[118:121]
	v_mfma_f32_16x16x32_bf16 v[184:187], v[188:191], v[136:139], v[94:97]
	v_mfma_f32_16x16x32_bf16 v[204:207], v[188:191], v[172:175], v[58:61]
	v_mfma_f32_16x16x32_bf16 v[208:211], v[192:195], v[172:175], v[54:57]
	v_mfma_f32_16x16x32_bf16 v[188:191], v[188:191], v[176:179], v[26:29]
	s_nop 2
	ds_read_b128 v[26:29], v130 offset:12288
	ds_read_b128 v[54:57], v130 offset:14336
	v_mfma_f32_16x16x32_bf16 v[114:117], v[192:195], v[132:135], v[114:117]
	v_mfma_f32_16x16x32_bf16 v[200:203], v[192:195], v[136:139], v[86:89]
	v_mfma_f32_16x16x32_bf16 v[192:195], v[192:195], v[176:179], v[22:25]
	v_add_u32_e32 v130, v160, v148
	s_waitcnt lgkmcnt(0)
	v_mfma_f32_16x16x32_bf16 v[212:215], v[196:199], v[172:175], v[30:33]
	ds_read_b128 v[22:25], v130
	ds_read_b128 v[86:89], v130 offset:2048
	s_nop 0
	v_add_u32_e32 v30, v159, v148
	v_mfma_f32_16x16x32_bf16 v[102:105], v[180:183], v[132:135], v[102:105]
	v_mfma_f32_16x16x32_bf16 v[74:77], v[180:183], v[136:139], v[74:77]
	v_mfma_f32_16x16x32_bf16 v[46:49], v[180:183], v[172:175], v[46:49]
	v_mfma_f32_16x16x32_bf16 v[10:13], v[180:183], v[176:179], v[10:13]
	ds_read_b128 v[180:183], v30
	ds_read_b128 v[216:219], v30 offset:2048
	ds_read_b128 v[220:223], v30 offset:4096
	ds_read_b128 v[224:227], v30 offset:6144
	v_mfma_f32_16x16x32_bf16 v[98:101], v[196:199], v[132:135], v[98:101]
	v_mfma_f32_16x16x32_bf16 v[66:69], v[196:199], v[136:139], v[66:69]
	v_mfma_f32_16x16x32_bf16 v[6:9], v[196:199], v[176:179], v[6:9]
	v_mfma_f32_16x16x32_bf16 v[196:199], v[26:29], v[172:175], v[18:21]
	v_mfma_f32_16x16x32_bf16 v[172:175], v[54:57], v[172:175], v[14:17]
	s_nop 2
	ds_read_b128 v[14:17], v130 offset:4096
	ds_read_b128 v[18:21], v130 offset:6144
	v_mfma_f32_16x16x32_bf16 v[70:73], v[26:29], v[132:135], v[70:73]
	v_mfma_f32_16x16x32_bf16 v[132:135], v[54:57], v[132:135], v[62:65]
	v_mfma_f32_16x16x32_bf16 v[38:41], v[26:29], v[136:139], v[38:41]
	v_mfma_f32_16x16x32_bf16 v[34:37], v[54:57], v[136:139], v[34:37]
	v_mfma_f32_16x16x32_bf16 v[2:5], v[26:29], v[176:179], v[2:5]
	v_mfma_f32_16x16x32_bf16 v[176:179], v[54:57], v[176:179], v[90:93]
	ds_read_b128 v[136:139], v130 offset:8192
	ds_read_b128 v[228:231], v130 offset:10240
	s_waitcnt lgkmcnt(0)
	v_mfma_f32_16x16x32_bf16 v[126:129], v[22:25], v[180:183], v[126:129]
	v_mfma_f32_16x16x32_bf16 v[122:125], v[86:89], v[180:183], v[122:125]
	v_mfma_f32_16x16x32_bf16 v[94:97], v[22:25], v[216:219], v[110:113]
	v_mfma_f32_16x16x32_bf16 v[90:93], v[86:89], v[216:219], v[106:109]
	v_mfma_f32_16x16x32_bf16 v[62:65], v[22:25], v[220:223], v[82:85]
	v_mfma_f32_16x16x32_bf16 v[58:61], v[86:89], v[220:223], v[78:81]
	v_mfma_f32_16x16x32_bf16 v[30:33], v[22:25], v[224:227], v[50:53]
	v_mfma_f32_16x16x32_bf16 v[26:29], v[86:89], v[224:227], v[42:45]
	v_mfma_f32_16x16x32_bf16 v[86:89], v[14:17], v[216:219], v[184:187]
	v_mfma_f32_16x16x32_bf16 v[22:25], v[14:17], v[224:227], v[188:191]
	s_nop 1
	ds_read_b128 v[184:187], v130 offset:12288
	ds_read_b128 v[188:191], v130 offset:14336
	v_mfma_f32_16x16x32_bf16 v[118:121], v[14:17], v[180:183], v[118:121]
	v_mfma_f32_16x16x32_bf16 v[114:117], v[18:21], v[180:183], v[114:117]
	v_mfma_f32_16x16x32_bf16 v[82:85], v[18:21], v[216:219], v[200:203]
	v_mfma_f32_16x16x32_bf16 v[54:57], v[14:17], v[220:223], v[204:207]
	v_mfma_f32_16x16x32_bf16 v[50:53], v[18:21], v[220:223], v[208:211]
	v_mfma_f32_16x16x32_bf16 v[18:21], v[18:21], v[224:227], v[192:195]
	v_mfma_f32_16x16x32_bf16 v[110:113], v[136:139], v[180:183], v[102:105]
	v_mfma_f32_16x16x32_bf16 v[106:109], v[228:231], v[180:183], v[98:101]
	v_mfma_f32_16x16x32_bf16 v[78:81], v[136:139], v[216:219], v[74:77]
	v_mfma_f32_16x16x32_bf16 v[74:77], v[228:231], v[216:219], v[66:69]
	v_mfma_f32_16x16x32_bf16 v[46:49], v[136:139], v[220:223], v[46:49]
	v_mfma_f32_16x16x32_bf16 v[42:45], v[228:231], v[220:223], v[212:215]
	v_mfma_f32_16x16x32_bf16 v[14:17], v[136:139], v[224:227], v[10:13]
	v_mfma_f32_16x16x32_bf16 v[6:9], v[228:231], v[224:227], v[6:9]
	s_nop 1
	v_mov_b32_e32 v10, v1
	s_waitcnt vmcnt(0) lgkmcnt(0)
	s_barrier
; __device__ __forceinline__ unsigned pack2(float a, float b) { unsigned r; asm("v_cvt_pk_bf16_f32 %0, %1, %2" : "=v"(r) : "v"(a), "v"(b)); return r; }
;   __device__ __forceinline__ float c4(int g, int rig, int col, f32x4 v) const {
;     ...
;     uint2 u; u.x = pack2(v[0], v[1]); u.y = pack2(v[2], v[3]);
;     *(uint2*)(out + row * ld + col) = u;
;     return v[0] * v[0] + v[1] * v[1] + v[2] * v[2] + v[3] * v[3];
;   }
;   __device__ __forceinline__ void rowsum(int g, int rig, int slot, float ss) const {
;     if (slot < nslots) part[(size_t)slot * ((size_t)8 * ostride) + (size_t)g * ostride + rig] = ss;
;   }
; template <bool SWAP, class Epi, bool THIN = false> ...
;     ...
;     if constexpr (Epi::KIND == 0) {
; #pragma unroll
;       for (int m = 0; m < 4; ++m) {
;         const int rig = rig0 + rw + m * 16 + fr_e;
;         if constexpr (Epi::ROWSUM) {
;           float ss = 0.f;
; #pragma unroll
;           for (int n = 0; n < 8; ++n) {
;             const int col = nt * 256 + wc_e * 128 + n * 16 + fq_e * 4;
;             if (col < N) ss += epi.c4(g, rig, col, acc[m][n]);
;           }
;           ss += __shfl_xor(ss, 16); ss += __shfl_xor(ss, 32);
;           if (fq_e == 0) epi.rowsum(g, rig, nt * 2 + wc_e, ss);
;         } else {
	v_mfma_f32_16x16x32_bf16 v[98:101], v[188:191], v[180:183], v[132:135]
	v_ashrrev_i32_e32 v11, 8, v10
	v_add_u32_e32 v11, s5, v11
	v_ashrrev_i32_e32 v12, 31, v11
	v_lshrrev_b32_e32 v12, 28, v12
	v_add_u32_e32 v12, v11, v12
	v_ashrrev_i32_e32 v138, 4, v12
	v_and_b32_e32 v132, 15, v10
	v_bfe_u32 v130, v10, 4, 2
	v_bfe_u32 v171, v10, 6, 1
	v_lshlrev_b32_e32 v12, 11, v138
	v_lshlrev_b32_e32 v11, 7, v11
	v_lshrrev_b32_e32 v10, 1, v10
	v_sub_u32_e32 v133, v11, v12
	v_and_b32_e32 v135, 64, v10
	v_lshlrev_b32_e32 v134, 7, v171
	v_mfma_f32_16x16x32_bf16 v[10:13], v[184:187], v[224:227], v[2:5]
	v_ashrrev_i32_e32 v139, 31, v138
	v_or3_b32 v132, v133, v135, v132
	v_ashrrev_i32_e32 v133, 31, v132
	v_lshlrev_b32_e32 v2, 2, v130
	v_mfma_f32_16x16x32_bf16 v[102:105], v[184:187], v[180:183], v[70:73]
	v_or3_b32 v134, v134, v2, s4
	v_lshlrev_b64 v[136:137], 21, v[138:139]
	v_cmp_gt_i32_e32 vcc, s29, v134
	v_mfma_f32_16x16x32_bf16 v[70:73], v[184:187], v[216:219], v[38:41]
	v_lshlrev_b64 v[140:141], 10, v[132:133]
	v_ashrrev_i32_e32 v135, 31, v134
	v_lshl_add_u64 v[136:137], s[38:39], 0, v[136:137]
	v_mfma_f32_16x16x32_bf16 v[66:69], v[188:191], v[216:219], v[34:37]
	v_mfma_f32_16x16x32_bf16 v[38:41], v[184:187], v[220:223], v[196:199]
	v_mfma_f32_16x16x32_bf16 v[34:37], v[188:191], v[220:223], v[172:175]
	v_mfma_f32_16x16x32_bf16 v[2:5], v[188:191], v[224:227], v[176:179]
	s_nop 1
	v_bfe_u32 v246, v1, 4, 1
	v_mul_u32_u24_e32 v246, 24, v246
	v_mov_b32_e32 v247, 0
	v_xor_b32_e32 v254, 16, v170
	v_lshlrev_b32_e32 v254, 2, v254
	v_xor_b32_e32 v255, 32, v170
	v_lshlrev_b32_e32 v255, 2, v255
	v_lshl_or_b32 v252, s20, 1, v171
	v_ashrrev_i32_e32 v253, 31, v252
	v_cmp_eq_u32_e64 s[18:19], 0, v130
	v_cmp_gt_i32_e64 s[20:21], 4, v252
	s_and_b64 s[18:19], s[18:19], s[20:21]
	v_lshlrev_b64 v[252:253], 16, v[252:253]
	v_lshl_add_u64 v[252:253], s[24:25], 0, v[252:253]
	v_lshlrev_b64 v[248:249], 13, v[138:139]
	v_lshl_add_u64 v[252:253], v[252:253], 0, v[248:249]
	v_lshl_add_u64 v[252:253], v[132:133], 2, v[252:253]
	v_lshl_add_u64 v[248:249], v[136:137], 0, v[140:141]
	v_lshl_add_u64 v[248:249], v[134:135], 1, v[248:249]
	v_lshl_add_u64 v[248:249], v[248:249], 0, v[246:247]
	v_cvt_pk_bf16_f32 v232, v126, v127
	v_cvt_pk_bf16_f32 v233, v128, v129
	v_mul_f32_e32 v240, v126, v126
	v_mul_f32_e32 v241, v127, v127
	v_mul_f32_e32 v242, v128, v128
	v_mul_f32_e32 v243, v129, v129
	v_add_f32_e32 v245, v240, v241
	v_add_f32_e32 v245, v242, v245
	v_add_f32_e32 v244, v243, v245
	v_cvt_pk_bf16_f32 v234, v122, v123
	v_cvt_pk_bf16_f32 v235, v124, v125
	v_mul_f32_e32 v240, v122, v122
	v_mul_f32_e32 v241, v123, v123
	v_mul_f32_e32 v242, v124, v124
	v_mul_f32_e32 v243, v125, v125
	v_add_f32_e32 v245, v240, v241
	v_add_f32_e32 v245, v242, v245
	v_add_f32_e32 v245, v243, v245
	v_add_f32_e32 v244, v245, v244
	s_nop 1
	v_permlane16_swap_b32 v232, v234
	v_permlane16_swap_b32 v233, v235
	global_store_dwordx4 v[248:249], v[232:235], off
	v_cvt_pk_bf16_f32 v236, v118, v119
	v_cvt_pk_bf16_f32 v237, v120, v121
	v_mul_f32_e32 v240, v118, v118
	v_mul_f32_e32 v241, v119, v119
	v_mul_f32_e32 v242, v120, v120
	v_mul_f32_e32 v243, v121, v121
	v_add_f32_e32 v245, v240, v241
	v_add_f32_e32 v245, v242, v245
	v_add_f32_e32 v245, v243, v245
	v_add_f32_e32 v244, v245, v244
	v_cvt_pk_bf16_f32 v238, v114, v115
	v_cvt_pk_bf16_f32 v239, v116, v117
	v_mul_f32_e32 v240, v114, v114
	v_mul_f32_e32 v241, v115, v115
	v_mul_f32_e32 v242, v116, v116
	v_mul_f32_e32 v243, v117, v117
	v_add_f32_e32 v245, v240, v241
	v_add_f32_e32 v245, v242, v245
	v_add_f32_e32 v245, v243, v245
	v_add_f32_e32 v244, v245, v244
	s_nop 1
	v_permlane16_swap_b32 v236, v238
	v_permlane16_swap_b32 v237, v239
	global_store_dwordx4 v[248:249], v[236:239], off offset:64
	v_cvt_pk_bf16_f32 v232, v110, v111
	v_cvt_pk_bf16_f32 v233, v112, v113
	v_mul_f32_e32 v240, v110, v110
	v_mul_f32_e32 v241, v111, v111
	v_mul_f32_e32 v242, v112, v112
	v_mul_f32_e32 v243, v113, v113
	v_add_f32_e32 v245, v240, v241
	v_add_f32_e32 v245, v242, v245
	v_add_f32_e32 v245, v243, v245
	v_add_f32_e32 v244, v245, v244
	v_cvt_pk_bf16_f32 v234, v106, v107
	v_cvt_pk_bf16_f32 v235, v108, v109
	v_mul_f32_e32 v240, v106, v106
	v_mul_f32_e32 v241, v107, v107
	v_mul_f32_e32 v242, v108, v108
	v_mul_f32_e32 v243, v109, v109
	v_add_f32_e32 v245, v240, v241
	v_add_f32_e32 v245, v242, v245
	v_add_f32_e32 v245, v243, v245
	v_add_f32_e32 v244, v245, v244
	s_nop 1
	v_permlane16_swap_b32 v232, v234
	v_permlane16_swap_b32 v233, v235
	global_store_dwordx4 v[248:249], v[232:235], off offset:128
	v_cvt_pk_bf16_f32 v236, v102, v103
	v_cvt_pk_bf16_f32 v237, v104, v105
	v_mul_f32_e32 v240, v102, v102
	v_mul_f32_e32 v241, v103, v103
	v_mul_f32_e32 v242, v104, v104
	v_mul_f32_e32 v243, v105, v105
	v_add_f32_e32 v245, v240, v241
	v_add_f32_e32 v245, v242, v245
	v_add_f32_e32 v245, v243, v245
	v_add_f32_e32 v244, v245, v244
	v_cvt_pk_bf16_f32 v238, v98, v99
	v_cvt_pk_bf16_f32 v239, v100, v101
	v_mul_f32_e32 v240, v98, v98
	v_mul_f32_e32 v241, v99, v99
	v_mul_f32_e32 v242, v100, v100
	v_mul_f32_e32 v243, v101, v101
	v_add_f32_e32 v245, v240, v241
	v_add_f32_e32 v245, v242, v245
	v_add_f32_e32 v245, v243, v245
	v_add_f32_e32 v244, v245, v244
	s_nop 1
	v_permlane16_swap_b32 v236, v238
	v_permlane16_swap_b32 v237, v239
	global_store_dwordx4 v[248:249], v[236:239], off offset:192
	ds_bpermute_b32 v251, v254, v244
	s_waitcnt lgkmcnt(0)
	v_add_f32_e32 v245, v244, v251
	ds_bpermute_b32 v251, v255, v245
	s_waitcnt lgkmcnt(0)
; __device__ __forceinline__ unsigned pack2(float a, float b) { unsigned r; asm("v_cvt_pk_bf16_f32 %0, %1, %2" : "=v"(r) : "v"(a), "v"(b)); return r; }
;   __device__ __forceinline__ float c4(int g, int rig, int col, f32x4 v) const {
;     ...
;     uint2 u; u.x = pack2(v[0], v[1]); u.y = pack2(v[2], v[3]);
;     *(uint2*)(out + row * ld + col) = u;
;     return v[0] * v[0] + v[1] * v[1] + v[2] * v[2] + v[3] * v[3];
;   }
;   __device__ __forceinline__ void rowsum(int g, int rig, int slot, float ss) const {
;     if (slot < nslots) part[(size_t)slot * ((size_t)8 * ostride) + (size_t)g * ostride + rig] = ss;
;   }
; template <bool SWAP, class Epi, bool THIN = false> ...
;     ...
;     if constexpr (Epi::KIND == 0) {
; #pragma unroll
;       for (int m = 0; m < 4; ++m) {
;         const int rig = rig0 + rw + m * 16 + fr_e;
;         if constexpr (Epi::ROWSUM) {
;           float ss = 0.f;
; #pragma unroll
;           for (int n = 0; n < 8; ++n) {
;             const int col = nt * 256 + wc_e * 128 + n * 16 + fq_e * 4;
;             if (col < N) ss += epi.c4(g, rig, col, acc[m][n]);
;           }
;           ss += __shfl_xor(ss, 16); ss += __shfl_xor(ss, 32);
;           if (fq_e == 0) epi.rowsum(g, rig, nt * 2 + wc_e, ss);
;         } else {
	v_add_f32_e32 v245, v245, v251
	s_and_saveexec_b64 s[20:21], s[18:19]
	global_store_dword v[252:253], v245, off
	s_or_b64 exec, exec, s[20:21]
	v_or_b32_e32 v248, 16, v132
	v_ashrrev_i32_e32 v249, 31, v248
	v_lshlrev_b64 v[248:249], 10, v[248:249]
	v_lshl_add_u64 v[248:249], v[136:137], 0, v[248:249]
	v_lshl_add_u64 v[248:249], v[134:135], 1, v[248:249]
	v_lshl_add_u64 v[248:249], v[248:249], 0, v[246:247]
	v_cvt_pk_bf16_f32 v232, v94, v95
	v_cvt_pk_bf16_f32 v233, v96, v97
	v_mul_f32_e32 v240, v94, v94
	v_mul_f32_e32 v241, v95, v95
	v_mul_f32_e32 v242, v96, v96
	v_mul_f32_e32 v243, v97, v97
	v_add_f32_e32 v245, v240, v241
	v_add_f32_e32 v245, v242, v245
	v_add_f32_e32 v244, v243, v245
	v_cvt_pk_bf16_f32 v234, v90, v91
	v_cvt_pk_bf16_f32 v235, v92, v93
	v_mul_f32_e32 v240, v90, v90
	v_mul_f32_e32 v241, v91, v91
	v_mul_f32_e32 v242, v92, v92
	v_mul_f32_e32 v243, v93, v93
	v_add_f32_e32 v245, v240, v241
	v_add_f32_e32 v245, v242, v245
	v_add_f32_e32 v245, v243, v245
	v_add_f32_e32 v244, v245, v244
	s_nop 1
	v_permlane16_swap_b32 v232, v234
	v_permlane16_swap_b32 v233, v235
	global_store_dwordx4 v[248:249], v[232:235], off
	v_cvt_pk_bf16_f32 v236, v86, v87
	v_cvt_pk_bf16_f32 v237, v88, v89
	v_mul_f32_e32 v240, v86, v86
	v_mul_f32_e32 v241, v87, v87
	v_mul_f32_e32 v242, v88, v88
	v_mul_f32_e32 v243, v89, v89
	v_add_f32_e32 v245, v240, v241
	v_add_f32_e32 v245, v242, v245
	v_add_f32_e32 v245, v243, v245
	v_add_f32_e32 v244, v245, v244
	v_cvt_pk_bf16_f32 v238, v82, v83
	v_cvt_pk_bf16_f32 v239, v84, v85
	v_mul_f32_e32 v240, v82, v82
	v_mul_f32_e32 v241, v83, v83
	v_mul_f32_e32 v242, v84, v84
	v_mul_f32_e32 v243, v85, v85
	v_add_f32_e32 v245, v240, v241
	v_add_f32_e32 v245, v242, v245
	v_add_f32_e32 v245, v243, v245
	v_add_f32_e32 v244, v245, v244
	s_nop 1
	v_permlane16_swap_b32 v236, v238
	v_permlane16_swap_b32 v237, v239
	global_store_dwordx4 v[248:249], v[236:239], off offset:64
	v_cvt_pk_bf16_f32 v232, v78, v79
	v_cvt_pk_bf16_f32 v233, v80, v81
	v_mul_f32_e32 v240, v78, v78
	v_mul_f32_e32 v241, v79, v79
	v_mul_f32_e32 v242, v80, v80
	v_mul_f32_e32 v243, v81, v81
	v_add_f32_e32 v245, v240, v241
	v_add_f32_e32 v245, v242, v245
	v_add_f32_e32 v245, v243, v245
	v_add_f32_e32 v244, v245, v244
	v_cvt_pk_bf16_f32 v234, v74, v75
	v_cvt_pk_bf16_f32 v235, v76, v77
	v_mul_f32_e32 v240, v74, v74
	v_mul_f32_e32 v241, v75, v75
	v_mul_f32_e32 v242, v76, v76
	v_mul_f32_e32 v243, v77, v77
	v_add_f32_e32 v245, v240, v241
	v_add_f32_e32 v245, v242, v245
	v_add_f32_e32 v245, v243, v245
	v_add_f32_e32 v244, v245, v244
	s_nop 1
	v_permlane16_swap_b32 v232, v234
	v_permlane16_swap_b32 v233, v235
	global_store_dwordx4 v[248:249], v[232:235], off offset:128
	v_cvt_pk_bf16_f32 v236, v70, v71
	v_cvt_pk_bf16_f32 v237, v72, v73
	v_mul_f32_e32 v240, v70, v70
	v_mul_f32_e32 v241, v71, v71
	v_mul_f32_e32 v242, v72, v72
	v_mul_f32_e32 v243, v73, v73
	v_add_f32_e32 v245, v240, v241
	v_add_f32_e32 v245, v242, v245
	v_add_f32_e32 v245, v243, v245
	v_add_f32_e32 v244, v245, v244
	v_cvt_pk_bf16_f32 v238, v66, v67
	v_cvt_pk_bf16_f32 v239, v68, v69
	v_mul_f32_e32 v240, v66, v66
	v_mul_f32_e32 v241, v67, v67
	v_mul_f32_e32 v242, v68, v68
	v_mul_f32_e32 v243, v69, v69
	v_add_f32_e32 v245, v240, v241
	v_add_f32_e32 v245, v242, v245
	v_add_f32_e32 v245, v243, v245
	v_add_f32_e32 v244, v245, v244
	s_nop 1
	v_permlane16_swap_b32 v236, v238
	v_permlane16_swap_b32 v237, v239
	global_store_dwordx4 v[248:249], v[236:239], off offset:192
	ds_bpermute_b32 v251, v254, v244
	s_waitcnt lgkmcnt(0)
	v_add_f32_e32 v245, v244, v251
	ds_bpermute_b32 v251, v255, v245
	s_waitcnt lgkmcnt(0)
	v_add_f32_e32 v245, v245, v251
	s_and_saveexec_b64 s[20:21], s[18:19]
	global_store_dword v[252:253], v245, off offset:64
	s_or_b64 exec, exec, s[20:21]
	v_or_b32_e32 v248, 32, v132
	v_ashrrev_i32_e32 v249, 31, v248
	v_lshlrev_b64 v[248:249], 10, v[248:249]
	v_lshl_add_u64 v[248:249], v[136:137], 0, v[248:249]
	v_lshl_add_u64 v[248:249], v[134:135], 1, v[248:249]
	v_lshl_add_u64 v[248:249], v[248:249], 0, v[246:247]
	v_cvt_pk_bf16_f32 v232, v62, v63
	v_cvt_pk_bf16_f32 v233, v64, v65
	v_mul_f32_e32 v240, v62, v62
	v_mul_f32_e32 v241, v63, v63
	v_mul_f32_e32 v242, v64, v64
	v_mul_f32_e32 v243, v65, v65
	v_add_f32_e32 v245, v240, v241
	v_add_f32_e32 v245, v242, v245
	v_add_f32_e32 v244, v243, v245
	v_cvt_pk_bf16_f32 v234, v58, v59
	v_cvt_pk_bf16_f32 v235, v60, v61
	v_mul_f32_e32 v240, v58, v58
	v_mul_f32_e32 v241, v59, v59
	v_mul_f32_e32 v242, v60, v60
	v_mul_f32_e32 v243, v61, v61
	v_add_f32_e32 v245, v240, v241
	v_add_f32_e32 v245, v242, v245
	v_add_f32_e32 v245, v243, v245
	v_add_f32_e32 v244, v245, v244
	s_nop 1
	v_permlane16_swap_b32 v232, v234
	v_permlane16_swap_b32 v233, v235
	global_store_dwordx4 v[248:249], v[232:235], off
	v_cvt_pk_bf16_f32 v236, v54, v55
	v_cvt_pk_bf16_f32 v237, v56, v57
	v_mul_f32_e32 v240, v54, v54
	v_mul_f32_e32 v241, v55, v55
	v_mul_f32_e32 v242, v56, v56
	v_mul_f32_e32 v243, v57, v57
	v_add_f32_e32 v245, v240, v241
	v_add_f32_e32 v245, v242, v245
	v_add_f32_e32 v245, v243, v245
	v_add_f32_e32 v244, v245, v244
	v_cvt_pk_bf16_f32 v238, v50, v51
	v_cvt_pk_bf16_f32 v239, v52, v53
	v_mul_f32_e32 v240, v50, v50
	v_mul_f32_e32 v241, v51, v51
	v_mul_f32_e32 v242, v52, v52
	v_mul_f32_e32 v243, v53, v53
	v_add_f32_e32 v245, v240, v241
	v_add_f32_e32 v245, v242, v245
	v_add_f32_e32 v245, v243, v245
	v_add_f32_e32 v244, v245, v244
	s_nop 1
	v_permlane16_swap_b32 v236, v238
	v_permlane16_swap_b32 v237, v239
	global_store_dwordx4 v[248:249], v[236:239], off offset:64
; __device__ __forceinline__ unsigned pack2(float a, float b) { unsigned r; asm("v_cvt_pk_bf16_f32 %0, %1, %2" : "=v"(r) : "v"(a), "v"(b)); return r; }
;   __device__ __forceinline__ float c4(int g, int rig, int col, f32x4 v) const {
;     ...
;     uint2 u; u.x = pack2(v[0], v[1]); u.y = pack2(v[2], v[3]);
;     *(uint2*)(out + row * ld + col) = u;
;     return v[0] * v[0] + v[1] * v[1] + v[2] * v[2] + v[3] * v[3];
;   }
;   __device__ __forceinline__ void rowsum(int g, int rig, int slot, float ss) const {
;     if (slot < nslots) part[(size_t)slot * ((size_t)8 * ostride) + (size_t)g * ostride + rig] = ss;
;   }
; template <bool SWAP, class Epi, bool THIN = false> ...
;     ...
;     if constexpr (Epi::KIND == 0) {
; #pragma unroll
;       for (int m = 0; m < 4; ++m) {
;         const int rig = rig0 + rw + m * 16 + fr_e;
;         if constexpr (Epi::ROWSUM) {
;           float ss = 0.f;
; #pragma unroll
;           for (int n = 0; n < 8; ++n) {
;             const int col = nt * 256 + wc_e * 128 + n * 16 + fq_e * 4;
;             if (col < N) ss += epi.c4(g, rig, col, acc[m][n]);
;           }
;           ss += __shfl_xor(ss, 16); ss += __shfl_xor(ss, 32);
;           if (fq_e == 0) epi.rowsum(g, rig, nt * 2 + wc_e, ss);
;         } else {
	v_cvt_pk_bf16_f32 v232, v46, v47
	v_cvt_pk_bf16_f32 v233, v48, v49
	v_mul_f32_e32 v240, v46, v46
	v_mul_f32_e32 v241, v47, v47
	v_mul_f32_e32 v242, v48, v48
	v_mul_f32_e32 v243, v49, v49
	v_add_f32_e32 v245, v240, v241
	v_add_f32_e32 v245, v242, v245
	v_add_f32_e32 v245, v243, v245
	v_add_f32_e32 v244, v245, v244
	v_cvt_pk_bf16_f32 v234, v42, v43
	v_cvt_pk_bf16_f32 v235, v44, v45
	v_mul_f32_e32 v240, v42, v42
	v_mul_f32_e32 v241, v43, v43
	v_mul_f32_e32 v242, v44, v44
	v_mul_f32_e32 v243, v45, v45
	v_add_f32_e32 v245, v240, v241
	v_add_f32_e32 v245, v242, v245
	v_add_f32_e32 v245, v243, v245
	v_add_f32_e32 v244, v245, v244
	s_nop 1
	v_permlane16_swap_b32 v232, v234
	v_permlane16_swap_b32 v233, v235
	global_store_dwordx4 v[248:249], v[232:235], off offset:128
	v_cvt_pk_bf16_f32 v236, v38, v39
	v_cvt_pk_bf16_f32 v237, v40, v41
	v_mul_f32_e32 v240, v38, v38
	v_mul_f32_e32 v241, v39, v39
	v_mul_f32_e32 v242, v40, v40
	v_mul_f32_e32 v243, v41, v41
	v_add_f32_e32 v245, v240, v241
	v_add_f32_e32 v245, v242, v245
	v_add_f32_e32 v245, v243, v245
	v_add_f32_e32 v244, v245, v244
	v_cvt_pk_bf16_f32 v238, v34, v35
	v_cvt_pk_bf16_f32 v239, v36, v37
	v_mul_f32_e32 v240, v34, v34
	v_mul_f32_e32 v241, v35, v35
	v_mul_f32_e32 v242, v36, v36
	v_mul_f32_e32 v243, v37, v37
	v_add_f32_e32 v245, v240, v241
	v_add_f32_e32 v245, v242, v245
	v_add_f32_e32 v245, v243, v245
	v_add_f32_e32 v244, v245, v244
	s_nop 1
	v_permlane16_swap_b32 v236, v238
	v_permlane16_swap_b32 v237, v239
	global_store_dwordx4 v[248:249], v[236:239], off offset:192
	ds_bpermute_b32 v251, v254, v244
	s_waitcnt lgkmcnt(0)
	v_add_f32_e32 v245, v244, v251
	ds_bpermute_b32 v251, v255, v245
	s_waitcnt lgkmcnt(0)
	v_add_f32_e32 v245, v245, v251
	s_and_saveexec_b64 s[20:21], s[18:19]
	global_store_dword v[252:253], v245, off offset:128
	s_or_b64 exec, exec, s[20:21]
	v_or_b32_e32 v248, 48, v132
	v_ashrrev_i32_e32 v249, 31, v248
	v_lshlrev_b64 v[248:249], 10, v[248:249]
	v_lshl_add_u64 v[248:249], v[136:137], 0, v[248:249]
	v_lshl_add_u64 v[248:249], v[134:135], 1, v[248:249]
	v_lshl_add_u64 v[248:249], v[248:249], 0, v[246:247]
	v_cvt_pk_bf16_f32 v232, v30, v31
	v_cvt_pk_bf16_f32 v233, v32, v33
	v_mul_f32_e32 v240, v30, v30
	v_mul_f32_e32 v241, v31, v31
	v_mul_f32_e32 v242, v32, v32
	v_mul_f32_e32 v243, v33, v33
	v_add_f32_e32 v245, v240, v241
	v_add_f32_e32 v245, v242, v245
	v_add_f32_e32 v244, v243, v245
	v_cvt_pk_bf16_f32 v234, v26, v27
	v_cvt_pk_bf16_f32 v235, v28, v29
	v_mul_f32_e32 v240, v26, v26
	v_mul_f32_e32 v241, v27, v27
	v_mul_f32_e32 v242, v28, v28
	v_mul_f32_e32 v243, v29, v29
	v_add_f32_e32 v245, v240, v241
	v_add_f32_e32 v245, v242, v245
	v_add_f32_e32 v245, v243, v245
	v_add_f32_e32 v244, v245, v244
	s_nop 1
	v_permlane16_swap_b32 v232, v234
	v_permlane16_swap_b32 v233, v235
	global_store_dwordx4 v[248:249], v[232:235], off
	v_cvt_pk_bf16_f32 v236, v22, v23
	v_cvt_pk_bf16_f32 v237, v24, v25
	v_mul_f32_e32 v240, v22, v22
	v_mul_f32_e32 v241, v23, v23
	v_mul_f32_e32 v242, v24, v24
	v_mul_f32_e32 v243, v25, v25
	v_add_f32_e32 v245, v240, v241
	v_add_f32_e32 v245, v242, v245
	v_add_f32_e32 v245, v243, v245
	v_add_f32_e32 v244, v245, v244
	v_cvt_pk_bf16_f32 v238, v18, v19
	v_cvt_pk_bf16_f32 v239, v20, v21
	v_mul_f32_e32 v240, v18, v18
	v_mul_f32_e32 v241, v19, v19
	v_mul_f32_e32 v242, v20, v20
	v_mul_f32_e32 v243, v21, v21
	v_add_f32_e32 v245, v240, v241
	v_add_f32_e32 v245, v242, v245
	v_add_f32_e32 v245, v243, v245
	v_add_f32_e32 v244, v245, v244
	s_nop 1
	v_permlane16_swap_b32 v236, v238
	v_permlane16_swap_b32 v237, v239
	global_store_dwordx4 v[248:249], v[236:239], off offset:64
	v_cvt_pk_bf16_f32 v232, v14, v15
	v_cvt_pk_bf16_f32 v233, v16, v17
	v_mul_f32_e32 v240, v14, v14
	v_mul_f32_e32 v241, v15, v15
	v_mul_f32_e32 v242, v16, v16
	v_mul_f32_e32 v243, v17, v17
	v_add_f32_e32 v245, v240, v241
	v_add_f32_e32 v245, v242, v245
	v_add_f32_e32 v245, v243, v245
	v_add_f32_e32 v244, v245, v244
	v_cvt_pk_bf16_f32 v234, v6, v7
	v_cvt_pk_bf16_f32 v235, v8, v9
	v_mul_f32_e32 v240, v6, v6
	v_mul_f32_e32 v241, v7, v7
	v_mul_f32_e32 v242, v8, v8
	v_mul_f32_e32 v243, v9, v9
	v_add_f32_e32 v245, v240, v241
	v_add_f32_e32 v245, v242, v245
	v_add_f32_e32 v245, v243, v245
	v_add_f32_e32 v244, v245, v244
	s_nop 1
	v_permlane16_swap_b32 v232, v234
	v_permlane16_swap_b32 v233, v235
	global_store_dwordx4 v[248:249], v[232:235], off offset:128
	v_cvt_pk_bf16_f32 v236, v10, v11
	v_cvt_pk_bf16_f32 v237, v12, v13
	v_mul_f32_e32 v240, v10, v10
	v_mul_f32_e32 v241, v11, v11
	v_mul_f32_e32 v242, v12, v12
	v_mul_f32_e32 v243, v13, v13
	v_add_f32_e32 v245, v240, v241
	v_add_f32_e32 v245, v242, v245
	v_add_f32_e32 v245, v243, v245
	v_add_f32_e32 v244, v245, v244
	v_cvt_pk_bf16_f32 v238, v2, v3
	v_cvt_pk_bf16_f32 v239, v4, v5
	v_mul_f32_e32 v240, v2, v2
	v_mul_f32_e32 v241, v3, v3
	v_mul_f32_e32 v242, v4, v4
	v_mul_f32_e32 v243, v5, v5
	v_add_f32_e32 v245, v240, v241
	v_add_f32_e32 v245, v242, v245
	v_add_f32_e32 v245, v243, v245
	v_add_f32_e32 v244, v245, v244
	s_nop 1
	v_permlane16_swap_b32 v236, v238
	v_permlane16_swap_b32 v237, v239
	global_store_dwordx4 v[248:249], v[236:239], off offset:192
	ds_bpermute_b32 v251, v254, v244
	s_waitcnt lgkmcnt(0)
	v_add_f32_e32 v245, v244, v251
	ds_bpermute_b32 v251, v255, v245
	s_waitcnt lgkmcnt(0)
	v_add_f32_e32 v245, v245, v251
	s_and_saveexec_b64 s[20:21], s[18:19]
	global_store_dword v[252:253], v245, off offset:192
	s_or_b64 exec, exec, s[20:21]
	s_mov_b64 s[4:5], exec
	s_branch .LBB0_337
